# pp_v21 + RC1 S3: the two lgkmcnt(0) waits between a wave's own LDS write and its dependent reads removed (same-wave LDS ops execute in order)
# baseline (speedup 1.0000x reference)
.LBB0_1108:
	v_pk_add_f32 v[14:15], v[38:39], v[14:15] op_sel:[1,0] op_sel_hi:[0,1] neg_lo:[0,1] neg_hi:[0,1]
	v_pk_add_f32 v[16:17], v[40:41], v[16:17] op_sel:[1,0] op_sel_hi:[0,1] neg_lo:[0,1] neg_hi:[0,1]
	v_cvt_pk_bf16_f32 v14, v14, v15
	v_cvt_pk_bf16_f32 v15, v16, v17
	v_add_u32_e32 v42, 0, v22
	ds_write_b64 v185, v[14:15]
	ds_read_b128 v[14:17], v42
	ds_read_b128 v[18:21], v186
	s_add_i32 s2, s2, -1
	s_waitcnt lgkmcnt(0)
	v_mfma_f32_16x16x32_bf16 v[14:17], v[14:17], v[18:21], 0
	v_add_u32_e32 v26, 0x1040, v26
	v_add_u32_e32 v25, 0x900, v25
	v_add_u32_e32 v24, 0x900, v24
	s_nop 4
	v_cvt_pk_bf16_f32 v14, v14, v15
	v_cvt_pk_bf16_f32 v15, v16, v17
	v_add_u32_e32 v16, 0, v23
	ds_write_b64 v16, v[14:15]
	v_add_u32_e32 v23, 32, v23
	v_add_u32_e32 v22, 0x400, v22
	v_add_u32_e32 v1, 0x900, v1
	s_cmp_eq_u32 s2, 0
	s_cbranch_scc1 .LBB0_1113
